# v010 plus next-tile prefetch: first 8 LDS-DMA loads of the next gemm8 tile issued after the staged tile read-back and before the 16 row stores, counted vmcnt(20)/(22)
# baseline (speedup 1.0000x reference)
; #define BAR __builtin_amdgcn_s_barrier()
; template <int EPI>
; __device__ void gemm8_phase(const Params& p, const u16* __restrict__ A, const u16* __restrict__ Bt, const int K, const int nN,
;                             unsigned char* smem, const int rep) {
;     ...
;   const int nM = T_TOK / BM8, nwg = nM * nN;
;   const int wid = (int)p.wv, lane = (int)p.tidx & 63, wr = wid >> 2, wc = wid & 3, fr = lane & 15, fq = lane >> 4;
;   const int nt = K / BK8;
;   const __amdgpu_buffer_rsrc_t rsrc_A = __builtin_amdgcn_make_buffer_rsrc((void*)A, (short)0, T_TOK * K * 2, 0x00020000);
;   const __amdgpu_buffer_rsrc_t rsrc_Bt = __builtin_amdgcn_make_buffer_rsrc((void*)Bt, (short)0, nN * 256 * K * 2, 0x00020000);
;   int voff0, voff1;
;   {
;     int r_, c_;
;     stage_rc((int)p.tidx * 16, r_, c_);
;     voff0 = (r_ * K + c_) * 2;
;     stage_rc((int)p.tidx * 16 + 8192, r_, c_);
;     voff1 = (r_ * K + c_) * 2;
;   }
;   for (int tile0 = blockIdx.x; tile0 < nwg * rep; tile0 += gridDim.x) {
;     const int tile = tile0 % nwg;
;     int wgid = tile;
;     {
;       int q = nwg / NXCD, r = nwg % NXCD, xcd = wgid % NXCD, off = wgid / NXCD;
;       wgid = (xcd < r ? xcd * (q + 1) : r * (q + 1) + (xcd - r) * q) + off;
;     }
;     const int nig = WGM * nN, gid = wgid / nig, fm = gid * WGM, gsz = min(nM - fm, WGM);
;     const int pm = fm + ((wgid % nig) % gsz), pn = (wgid % nig) / gsz, brow = pm * BM8, bcol = pn * BM8;
;     f32x4 acc[2][2][4][2];
; #pragma unroll
;     for (int a = 0; a < 2; ++a)
; #pragma unroll
;       for (int b = 0; b < 2; ++b)
; #pragma unroll
;         for (int m = 0; m < 4; ++m)
; #pragma unroll
;           for (int n = 0; n < 2; ++n) acc[a][b][m][n] = (f32x4){0.f, 0.f, 0.f, 0.f};
;     bf16x8 At[4][2], B0[2][2], B1[2][2];
;     STAGE(SB(0, 0), Bt, bcol, 0); STAGE(SA(0, 0), A, brow, 0);
;     STAGE(SB(0, 1), Bt, bcol + HALF, 0); STAGE(SA(0, 1), A, brow + HALF, 0);
;     if (wr == 1) BAR;
.LBB0_195:
	s_cmp_lt_i32 s86, 2
	s_cselect_b64 s[0:1], -1, 0
	s_cmp_gt_i32 s88, 0
	s_cselect_b64 s[2:3], -1, 0
	s_and_b64 s[0:1], s[0:1], s[2:3]
	s_andn2_b64 vcc, exec, s[0:1]
	s_mov_b32 s1, 0
	s_cbranch_vccnz .LBB0_412
	s_mov_b64 s[2:3], 0
	s_add_u32 s8, s84, s2
	s_addc_u32 s22, s85, s3
	s_and_b32 s0, s90, 2
	v_mbcnt_lo_u32_b32 v0, -1, 0
	s_cmp_eq_u64 s[0:1], 0
	s_movk_i32 s0, 0x660
	v_readlane_b32 s2, v255, 6
	v_mbcnt_hi_u32_b32 v195, -1, v0
	s_cselect_b32 s23, s0, 0xcc0
	s_cmp_ge_i32 s78, s23
	v_lshl_add_u32 v252, s2, 6, v195
	s_cbranch_scc1 .LBB0_237
	v_bfe_i32 v1, v252, 27, 1
	v_lshlrev_b32_e32 v138, 4, v252
	v_lshrrev_b32_e32 v1, 22, v1
	v_add_u32_e32 v1, v138, v1
	v_and_b32_e32 v1, 0xfffffc00, v1
	v_sub_u32_e32 v1, v138, v1
	v_lshrrev_b32_e32 v2, 4, v1
	v_bitop3_b32 v1, v2, v1, 32 bitop3:0x6c
	v_ashrrev_i32_e32 v0, 31, v252
	v_ashrrev_i32_e32 v3, 31, v1
	v_lshrrev_b32_e32 v0, 26, v0
	v_lshrrev_b32_e32 v3, 26, v3
	v_add_u32_e32 v0, v252, v0
	v_add_u32_e32 v3, v1, v3
	v_ashrrev_i32_e32 v0, 6, v0
	v_lshrrev_b32_e32 v4, 6, v3
	v_and_b32_e32 v3, 0xc0, v3
	v_lshlrev_b32_e32 v2, 3, v0
	v_lshlrev_b32_e32 v0, 5, v0
	v_sub_u32_e32 v1, v1, v3
	v_mov_b32_e32 v3, 1
	v_and_b32_e32 v2, 0x1ffff0, v2
	v_and_b32_e32 v0, 32, v0
	v_ashrrev_i16_sdwa v1, v3, sext(v1) dst_sel:DWORD dst_unused:UNUSED_PAD src0_sel:DWORD src1_sel:BYTE_0
	v_add_u32_sdwa v0, v0, sext(v1) dst_sel:DWORD dst_unused:UNUSED_PAD src0_sel:DWORD src1_sel:WORD_0
	v_add_lshl_u32 v1, v4, v2, 11
	v_add_u32_e32 v140, 0x2000, v138
	v_lshl_add_u32 v139, v0, 1, v1
	v_ashrrev_i32_e32 v0, 31, v140
	v_lshrrev_b32_e32 v0, 22, v0
	v_add_u32_e32 v0, v140, v0
	v_ashrrev_i32_e32 v0, 10, v0
	v_mul_i32_i24_e32 v1, 0x400, v0
	v_sub_u32_e32 v1, v140, v1
	v_lshrrev_b32_e32 v2, 4, v1
	v_bitop3_b32 v1, v2, v1, 32 bitop3:0x6c
	v_ashrrev_i32_e32 v4, 31, v1
	v_lshrrev_b32_e32 v4, 26, v4
	v_add_u32_e32 v4, v1, v4
	v_lshrrev_b32_e32 v5, 6, v4
	v_and_b32_e32 v4, 0xc0, v4
	v_lshlrev_b32_e32 v2, 3, v0
	v_lshlrev_b32_e32 v0, 5, v0
	v_sub_u32_e32 v1, v1, v4
	s_add_u32 s12, s8, 0x2242000
	v_and_b32_e32 v2, 0x1ffff0, v2
	v_and_b32_e32 v0, 32, v0
	v_ashrrev_i16_sdwa v1, v3, sext(v1) dst_sel:DWORD dst_unused:UNUSED_PAD src0_sel:DWORD src1_sel:BYTE_0
	s_addc_u32 s0, s22, 0
	v_add_u32_sdwa v0, v0, sext(v1) dst_sel:DWORD dst_unused:UNUSED_PAD src0_sel:DWORD src1_sel:WORD_0
	v_add_lshl_u32 v1, v5, v2, 11
	s_and_b32 s13, s0, 0xffff
	s_and_b32 s9, s22, 0xffff
	v_lshl_add_u32 v141, v0, 1, v1
	v_and_b32_e32 v0, 15, v195
	v_bfe_u32 v1, v252, 4, 2
	s_and_b32 s3, s2, 3
	s_ashr_i32 s4, s2, 2
	s_cmp_eq_u32 s4, 1
	v_lshlrev_b32_e32 v2, 4, v1
	v_lshlrev_b32_e32 v3, 6, v0
	v_lshlrev_b32_e32 v5, 2, v195
	s_cselect_b64 s[0:1], -1, 0
	s_lshl_b32 s5, s3, 12
	v_or_b32_e32 v4, v2, v3
	v_and_b32_e32 v5, 32, v5
	s_mov_b32 s6, 0x10000
	v_bitop3_b32 v6, v4, s6, v5 bitop3:0xde
	s_mov_b32 s6, 0x14000
	s_cmp_lt_u32 s2, 4
	v_bitop3_b32 v7, v4, s6, v5 bitop3:0xde
	s_mov_b32 s6, 0x18000
	s_cselect_b64 s[16:17], -1, 0
	s_lshl_b32 s24, s3, 5
	v_bitop3_b32 v8, v4, s6, v5 bitop3:0xde
	s_mov_b32 s6, 0x1c000
	v_lshlrev_b32_e32 v1, 2, v1
	s_lshl_b32 s2, s4, 13
	s_or_b32 s25, s24, 0x80
	v_bitop3_b32 v4, v4, s6, v5 bitop3:0xde
	v_lshl_or_b32 v142, s4, 6, v1
	s_or_b32 s4, s2, 0x800
	s_or_b32 s6, s2, 0x1000
	s_or_b32 s7, s2, 0x1800
	v_lshl_or_b32 v144, s3, 4, v0
	s_lshr_b32 s3, s25, 1
	v_lshlrev_b32_e32 v10, 6, v195
	s_add_u32 s18, s8, 0x4442000
	v_lshrrev_b32_e32 v9, 2, v252
	v_and_b32_e32 v10, 0x3c0, v10
	s_addc_u32 s19, s22, 0
	s_mov_b32 s15, 0x20000
	v_bitop3_b32 v3, v2, v5, v3 bitop3:0x36
	v_or_b32_e32 v143, s24, v0
	v_and_b32_e32 v9, 4, v9
	v_bitop3_b32 v2, v10, v5, v2 bitop3:0x36
	v_mov_b32_e32 v145, 0x800
	v_or_b32_e32 v147, s3, v0
	s_add_u32 s20, s8, 0x2040000
	v_cndmask_b32_e64 v0, 0, 1, s[0:1]
	s_mov_b32 s14, 0x2200000
	s_mov_b32 s10, 0xc00000
	s_mov_b32 s11, s15
	v_and_or_b32 v146, v1, 4, v145
	v_or_b32_e32 v148, 0x800, v9
	v_or_b32_e32 v149, 0x801, v9
	v_or_b32_e32 v150, 0x802, v9
	v_or_b32_e32 v151, 0x803, v9
	v_add_u32_e32 v152, 0x10000, v138
	v_add_u32_e32 v153, 0x12000, v138
	v_add_u32_e32 v154, 0x14000, v138
	v_add_u32_e32 v155, 0x16000, v138
	s_movk_i32 s26, 0x4000
	v_add_u32_e32 v156, 0x4000, v138
	v_add_u32_e32 v157, 0x6000, v138
	v_add_u32_e32 v158, 0x18000, v138
	v_add_u32_e32 v159, 0x1a000, v138
	v_add_u32_e32 v160, 0x8000, v138
	v_add_u32_e32 v161, 0xa000, v138
	v_add_u32_e32 v162, 0x1c000, v138
	v_add_u32_e32 v163, 0x1e000, v138
	v_add_u32_e32 v164, 0xc000, v138
	v_add_u32_e32 v165, 0xe000, v138
	s_addc_u32 s21, s22, 0
	s_movk_i32 s27, 0xcd
	v_add_u32_e32 v166, s5, v6
	v_add_u32_e32 v167, s2, v3
	v_add_u32_e32 v168, s4, v2
	v_add_u32_e32 v169, s6, v2
	v_add_u32_e32 v170, s7, v2
	v_add_u32_e32 v171, s5, v7
	v_add_u32_e32 v172, s5, v8
	v_add_u32_e32 v173, s5, v4
	s_movk_i32 s28, 0x3080
	v_mov_b32_e32 v129, 0
	s_movk_i32 s29, 0x7cd
	s_movk_i32 s30, 0x7ce
	s_movk_i32 s31, 0x7cf
	s_movk_i32 s34, 0x7dd
	s_movk_i32 s35, 0x7de
	s_movk_i32 s36, 0x7df
	s_movk_i32 s37, 0x7ed
	s_movk_i32 s38, 0x7ee
	s_movk_i32 s39, 0x7ef
	s_movk_i32 s40, 0x7fd
	s_movk_i32 s41, 0x7fe
	s_movk_i32 s42, 0x7ff
	v_cmp_ne_u32_e64 s[2:3], 1, v0
	s_mov_b32 s43, s78
	s_branch .LBB0_199
.LBB0_199:
	s_mul_hi_i32 s0, s43, 0xa0a0a0a1
	s_add_i32 s0, s0, s43
	s_lshr_b32 s1, s0, 31
	s_lshr_b32 s0, s0, 10
	s_add_i32 s0, s0, s1
	s_mulk_i32 s0, 0x660
	s_sub_i32 s0, s43, s0
	s_sext_i32_i16 s1, s0
	s_bfe_u32 s1, s1, 0x3001c
	s_add_i32 s1, s0, s1
	s_sext_i32_i16 s4, s1
	s_and_b32 s1, s1, 0xfff8
	s_sub_i32 s0, s0, s1
	s_ashr_i32 s4, s4, 3
	s_sext_i32_i16 s1, s0
	s_cmp_lt_i32 s1, 0
	s_cselect_b32 s1, s27, 0xcc
	s_mul_i32 s0, s1, s0
	s_add_i32 s0, s0, s4
	s_sext_i32_i16 s1, s0
	s_mulk_i32 s1, 0x2aab
	s_lshr_b32 s4, s1, 31
	s_ashr_i32 s7, s1, 20
	s_add_i32 s7, s7, s4
	s_mul_i32 s1, s7, 0x60
	s_sub_i32 s0, s0, s1
	s_bfe_i32 s1, s0, 0x80000
	s_bfe_u32 s1, s1, 0x2000d
	s_add_i32 s1, s0, s1
	s_bfe_i32 s5, s1, 0x80000
	s_and_b32 s1, s1, 0xfc
	s_sext_i32_i16 s5, s5
	s_sub_i32 s1, s0, s1
	s_sext_i32_i8 s33, s1
	s_ashr_i32 s1, s5, 2
	v_readfirstlane_b32 s5, v152
	s_lshl_b32 s4, s7, 2
	s_lshl_b32 s6, s1, 19
	s_mov_b32 m0, s5
	v_readfirstlane_b32 s5, v153
	s_add_i32 s4, s4, s33
	buffer_load_dwordx4 v139, s[8:11], s6 offen lds
	s_mov_b32 m0, s5
	v_readfirstlane_b32 s44, v138
	buffer_load_dwordx4 v141, s[8:11], s6 offen lds
	s_lshl_b32 s5, s4, 19
	s_mov_b32 m0, s44
	v_readfirstlane_b32 s44, v140
	buffer_load_dwordx4 v139, s[12:15], s5 offen lds
	s_mov_b32 m0, s44
	v_readfirstlane_b32 s45, v154
	buffer_load_dwordx4 v141, s[12:15], s5 offen lds
	s_or_b32 s44, s6, 0x40000
	s_mov_b32 m0, s45
	v_readfirstlane_b32 s45, v155
	buffer_load_dwordx4 v139, s[8:11], s44 offen lds
	s_mov_b32 m0, s45
	v_readfirstlane_b32 s45, v156
	buffer_load_dwordx4 v141, s[8:11], s44 offen lds
	s_or_b32 s44, s5, 0x40000
	s_mov_b32 m0, s45
	v_readfirstlane_b32 s45, v157
	buffer_load_dwordx4 v139, s[12:15], s44 offen lds
	s_mov_b32 m0, s45
	s_and_b64 vcc, exec, s[2:3]
	buffer_load_dwordx4 v141, s[12:15], s44 offen lds
	s_cbranch_vccnz .LBB0_201
	s_barrier

; template <int EPI>
; __device__ void gemm8_phase(const Params& p, const u16* __restrict__ A, const u16* __restrict__ Bt, const int K, const int nN,
;                             unsigned char* smem, const int rep) {
;     ...
;   for (int tile0 = blockIdx.x; tile0 < nwg * rep; tile0 += gridDim.x) {
;     const int tile = tile0 % nwg;
;     int wgid = tile;
;     {
;       int q = nwg / NXCD, r = nwg % NXCD, xcd = wgid % NXCD, off = wgid / NXCD;
;       wgid = (xcd < r ? xcd * (q + 1) : r * (q + 1) + (xcd - r) * q) + off;
;     }
;     const int nig = WGM * nN, gid = wgid / nig, fm = gid * WGM, gsz = min(nM - fm, WGM);
;     const int pm = fm + ((wgid % nig) % gsz), pn = (wgid % nig) / gsz, brow = pm * BM8, bcol = pn * BM8;
;     ...
;     STAGE(SB(0, 0), Bt, bcol, 0); STAGE(SA(0, 0), A, brow, 0);
;     STAGE(SB(0, 1), Bt, bcol + HALF, 0); STAGE(SA(0, 1), A, brow + HALF, 0);
.Lg1_readback:
	s_waitcnt lgkmcnt(0)
	s_barrier
	v_readlane_b32 s7, v255, 6
	v_lshrrev_b32_e32 v178, 5, v195
	v_and_b32_e32 v176, 31, v195
	s_lshl_b32 s7, s7, 5
	v_add_u32_e32 v178, s7, v178
	v_lshlrev_b32_e32 v176, 4, v176
	v_add_u32_e32 v177, s4, v178
	v_mul_u32_u24_e32 v177, 0x3080, v177
	v_mul_u32_u24_e32 v178, 0x210, v178
	v_add3_u32 v177, v177, v176, s33
	v_add_u32_e32 v176, v178, v176
	ds_read_b128 v[0:3], v176
	ds_read_b128 v[4:7], v176 offset:1056
	ds_read_b128 v[8:11], v176 offset:2112
	ds_read_b128 v[12:15], v176 offset:3168
	ds_read_b128 v[16:19], v176 offset:4224
	ds_read_b128 v[20:23], v176 offset:5280
	ds_read_b128 v[24:27], v176 offset:6336
	ds_read_b128 v[28:31], v176 offset:7392
	ds_read_b128 v[32:35], v176 offset:8448
	ds_read_b128 v[36:39], v176 offset:9504
	ds_read_b128 v[40:43], v176 offset:10560
	ds_read_b128 v[44:47], v176 offset:11616
	ds_read_b128 v[48:51], v176 offset:12672
	ds_read_b128 v[52:55], v176 offset:13728
	ds_read_b128 v[56:59], v176 offset:14784
	ds_read_b128 v[60:63], v176 offset:15840
	s_waitcnt lgkmcnt(0)
	s_barrier
	s_add_i32 s43, s43, s96
	s_cmp_lt_i32 s43, s23
	s_cbranch_scc0 .Lstg1
	s_mul_hi_i32 s0, s43, 0xa0a0a0a1
	s_add_i32 s0, s0, s43
	s_lshr_b32 s1, s0, 31
	s_lshr_b32 s0, s0, 10
	s_add_i32 s0, s0, s1
	s_mulk_i32 s0, 0x660
	s_sub_i32 s0, s43, s0
	s_sext_i32_i16 s1, s0
	s_bfe_u32 s1, s1, 0x3001c
	s_add_i32 s1, s0, s1
	s_sext_i32_i16 s4, s1
	s_and_b32 s1, s1, 0xfff8
	s_sub_i32 s0, s0, s1
	s_ashr_i32 s4, s4, 3
	s_sext_i32_i16 s1, s0
	s_cmp_lt_i32 s1, 0
	s_cselect_b32 s1, s27, 0xcc
	s_mul_i32 s0, s1, s0
	s_add_i32 s0, s0, s4
	s_sext_i32_i16 s1, s0
	s_mulk_i32 s1, 0x2aab
	s_lshr_b32 s4, s1, 31
	s_ashr_i32 s7, s1, 20
	s_add_i32 s7, s7, s4
	s_mul_i32 s1, s7, 0x60
	s_sub_i32 s0, s0, s1
	s_bfe_i32 s1, s0, 0x80000
	s_bfe_u32 s1, s1, 0x2000d
	s_add_i32 s1, s0, s1
	s_bfe_i32 s5, s1, 0x80000
	s_and_b32 s1, s1, 0xfc
	s_sext_i32_i16 s5, s5
	s_sub_i32 s1, s0, s1
	s_sext_i32_i8 s33, s1
	s_ashr_i32 s1, s5, 2
	v_readfirstlane_b32 s5, v152
	s_lshl_b32 s4, s7, 2
	s_lshl_b32 s6, s1, 19
	s_mov_b32 m0, s5
	v_readfirstlane_b32 s5, v153
	s_add_i32 s4, s4, s33
	buffer_load_dwordx4 v139, s[8:11], s6 offen lds
	s_mov_b32 m0, s5
	v_readfirstlane_b32 s44, v138
	buffer_load_dwordx4 v141, s[8:11], s6 offen lds
	s_lshl_b32 s5, s4, 19
	s_mov_b32 m0, s44
	v_readfirstlane_b32 s44, v140
	buffer_load_dwordx4 v139, s[12:15], s5 offen lds
	s_mov_b32 m0, s44
	v_readfirstlane_b32 s45, v154
	buffer_load_dwordx4 v141, s[12:15], s5 offen lds
	s_or_b32 s44, s6, 0x40000
	s_mov_b32 m0, s45
	v_readfirstlane_b32 s45, v155
	buffer_load_dwordx4 v139, s[8:11], s44 offen lds
	s_mov_b32 m0, s45
	v_readfirstlane_b32 s45, v156
	buffer_load_dwordx4 v141, s[8:11], s44 offen lds
	s_or_b32 s44, s5, 0x40000
	s_mov_b32 m0, s45
	v_readfirstlane_b32 s45, v157
	buffer_load_dwordx4 v139, s[12:15], s44 offen lds
	s_mov_b32 m0, s45
	s_and_b64 vcc, exec, s[2:3]
	buffer_load_dwordx4 v141, s[12:15], s44 offen lds
.Lstg1:
	global_store_dwordx4 v177, v[0:3], s[18:19]
	v_add_u32_e32 v177, 0x6100, v177
	global_store_dwordx4 v177, v[4:7], s[18:19]
	v_add_u32_e32 v177, 0x6100, v177
	global_store_dwordx4 v177, v[8:11], s[18:19]
	v_add_u32_e32 v177, 0x6100, v177
	global_store_dwordx4 v177, v[12:15], s[18:19]
	v_add_u32_e32 v177, 0x6100, v177
	global_store_dwordx4 v177, v[16:19], s[18:19]
	v_add_u32_e32 v177, 0x6100, v177
	global_store_dwordx4 v177, v[20:23], s[18:19]
	v_add_u32_e32 v177, 0x6100, v177
	global_store_dwordx4 v177, v[24:27], s[18:19]
	v_add_u32_e32 v177, 0x6100, v177
	global_store_dwordx4 v177, v[28:31], s[18:19]
	v_add_u32_e32 v177, 0x6100, v177
	global_store_dwordx4 v177, v[32:35], s[18:19]
	v_add_u32_e32 v177, 0x6100, v177
	global_store_dwordx4 v177, v[36:39], s[18:19]
	v_add_u32_e32 v177, 0x6100, v177
	global_store_dwordx4 v177, v[40:43], s[18:19]
	v_add_u32_e32 v177, 0x6100, v177
	global_store_dwordx4 v177, v[44:47], s[18:19]
	v_add_u32_e32 v177, 0x6100, v177
	global_store_dwordx4 v177, v[48:51], s[18:19]
	v_add_u32_e32 v177, 0x6100, v177
	global_store_dwordx4 v177, v[52:55], s[18:19]
	v_add_u32_e32 v177, 0x6100, v177
	global_store_dwordx4 v177, v[56:59], s[18:19]
	v_add_u32_e32 v177, 0x6100, v177
	global_store_dwordx4 v177, v[60:63], s[18:19]
	s_cmp_lt_i32 s43, s23
	s_cbranch_scc0 .LBB0_237
	s_and_b64 vcc, exec, s[2:3]
	s_cbranch_vccnz .Lpf1_201
	s_barrier
; #define WAIT_V(n) asm volatile("s_waitcnt vmcnt(" #n ")" ::: "memory")
; #define BAR __builtin_amdgcn_s_barrier()
; template <int EPI>
; __device__ void gemm8_phase(const Params& p, const u16* __restrict__ A, const u16* __restrict__ Bt, const int K, const int nN,
;                             unsigned char* smem, const int rep) {
;     ...
;     if (wr == 1) BAR;
;     WAIT_V(4); BAR;
;     STAGE(SB(1, 0), Bt, bcol, 1); STAGE(SA(1, 0), A, brow, 1); STAGE(SB(1, 1), Bt, bcol + HALF, 1);
;     WAIT_V(6); BAR;
.Lpf1_201:
	v_readfirstlane_b32 s45, v158
	s_or_b32 s44, s6, 0x80
	s_mov_b32 m0, s45
	v_readfirstlane_b32 s45, v159
	s_waitcnt vmcnt(20)
	s_barrier
	buffer_load_dwordx4 v139, s[8:11], s44 offen lds
	s_mov_b32 m0, s45
	v_readfirstlane_b32 s45, v160
	buffer_load_dwordx4 v141, s[8:11], s44 offen lds
	s_or_b32 s44, s5, 0x80
	s_mov_b32 m0, s45
	v_readfirstlane_b32 s45, v161
	buffer_load_dwordx4 v139, s[12:15], s44 offen lds
	s_mov_b32 m0, s45
	v_readfirstlane_b32 s45, v162
	buffer_load_dwordx4 v141, s[12:15], s44 offen lds
	s_or_b32 s44, s6, 0x40080
	s_mov_b32 m0, s45
	v_readfirstlane_b32 s45, v163
	buffer_load_dwordx4 v139, s[8:11], s44 offen lds
	s_mov_b32 m0, s45
	s_lshl_b32 s7, s7, 21
	buffer_load_dwordx4 v141, s[8:11], s44 offen lds
	s_waitcnt vmcnt(22)
	s_lshl_b32 s33, s33, 19
	v_mov_b32_e32 v0, 0
	s_add_i32 s7, s7, s33
	s_mov_b32 s33, -2
	s_mov_b32 s44, 0
	v_mov_b32_e32 v1, v0
	v_mov_b32_e32 v2, v0
	v_mov_b32_e32 v3, v0
	v_mov_b32_e32 v4, v0
	v_mov_b32_e32 v5, v0
	v_mov_b32_e32 v6, v0
	v_mov_b32_e32 v7, v0
	v_mov_b32_e32 v8, v0
	v_mov_b32_e32 v9, v0
	v_mov_b32_e32 v10, v0
	v_mov_b32_e32 v11, v0
	v_mov_b32_e32 v12, v0
	v_mov_b32_e32 v13, v0
	v_mov_b32_e32 v14, v0
	v_mov_b32_e32 v15, v0
	v_mov_b32_e32 v16, v0
	v_mov_b32_e32 v17, v0
	v_mov_b32_e32 v18, v0
	v_mov_b32_e32 v19, v0
	v_mov_b32_e32 v20, v0
	v_mov_b32_e32 v21, v0
	v_mov_b32_e32 v22, v0
	v_mov_b32_e32 v23, v0
	v_mov_b32_e32 v24, v0
	v_mov_b32_e32 v25, v0
	v_mov_b32_e32 v26, v0
	v_mov_b32_e32 v27, v0
	v_mov_b32_e32 v28, v0
	v_mov_b32_e32 v29, v0
	v_mov_b32_e32 v30, v0
	v_mov_b32_e32 v31, v0
	v_mov_b32_e32 v32, v0
	v_mov_b32_e32 v33, v0
	v_mov_b32_e32 v34, v0
	v_mov_b32_e32 v35, v0
	v_mov_b32_e32 v36, v0
	v_mov_b32_e32 v37, v0
	v_mov_b32_e32 v38, v0
	v_mov_b32_e32 v39, v0
	v_mov_b32_e32 v40, v0
	v_mov_b32_e32 v41, v0
	v_mov_b32_e32 v42, v0
	v_mov_b32_e32 v43, v0
	v_mov_b32_e32 v44, v0
	v_mov_b32_e32 v45, v0
	v_mov_b32_e32 v46, v0
	v_mov_b32_e32 v47, v0
	v_mov_b32_e32 v48, v0
	v_mov_b32_e32 v49, v0
	v_mov_b32_e32 v50, v0
	v_mov_b32_e32 v51, v0
	v_mov_b32_e32 v52, v0
	v_mov_b32_e32 v53, v0
	v_mov_b32_e32 v54, v0
	v_mov_b32_e32 v55, v0
	v_mov_b32_e32 v56, v0
	v_mov_b32_e32 v57, v0
	v_mov_b32_e32 v58, v0
	v_mov_b32_e32 v59, v0
	v_mov_b32_e32 v60, v0
	v_mov_b32_e32 v61, v0
	v_mov_b32_e32 v62, v0
	v_mov_b32_e32 v63, v0
	v_mov_b32_e32 v64, v0
	v_mov_b32_e32 v65, v0
	v_mov_b32_e32 v66, v0
	v_mov_b32_e32 v67, v0
	v_mov_b32_e32 v68, v0
	v_mov_b32_e32 v69, v0
	v_mov_b32_e32 v70, v0
	v_mov_b32_e32 v71, v0
	v_mov_b32_e32 v72, v0
	v_mov_b32_e32 v73, v0
	v_mov_b32_e32 v74, v0
	v_mov_b32_e32 v75, v0
	v_mov_b32_e32 v76, v0
	v_mov_b32_e32 v77, v0
	v_mov_b32_e32 v78, v0
	v_mov_b32_e32 v79, v0
	v_mov_b32_e32 v80, v0
	v_mov_b32_e32 v81, v0
	v_mov_b32_e32 v82, v0
	v_mov_b32_e32 v83, v0
	v_mov_b32_e32 v84, v0
	v_mov_b32_e32 v85, v0
	v_mov_b32_e32 v86, v0
	v_mov_b32_e32 v87, v0
	v_mov_b32_e32 v88, v0
	v_mov_b32_e32 v89, v0
	v_mov_b32_e32 v90, v0
	v_mov_b32_e32 v91, v0
	v_mov_b32_e32 v92, v0
	v_mov_b32_e32 v93, v0
	v_mov_b32_e32 v94, v0
	v_mov_b32_e32 v95, v0
	v_mov_b32_e32 v96, v0
	v_mov_b32_e32 v97, v0
	v_mov_b32_e32 v98, v0
	v_mov_b32_e32 v99, v0
	v_mov_b32_e32 v100, v0
	v_mov_b32_e32 v101, v0
	v_mov_b32_e32 v102, v0
	v_mov_b32_e32 v103, v0
	v_mov_b32_e32 v104, v0
	v_mov_b32_e32 v105, v0
	v_mov_b32_e32 v106, v0
	v_mov_b32_e32 v107, v0
	v_mov_b32_e32 v108, v0
	v_mov_b32_e32 v109, v0
	v_mov_b32_e32 v110, v0
	v_mov_b32_e32 v111, v0
	v_mov_b32_e32 v112, v0
	v_mov_b32_e32 v113, v0
	v_mov_b32_e32 v114, v0
	v_mov_b32_e32 v115, v0
	v_mov_b32_e32 v116, v0
	v_mov_b32_e32 v117, v0
	v_mov_b32_e32 v118, v0
	v_mov_b32_e32 v119, v0
	v_mov_b32_e32 v120, v0
	v_mov_b32_e32 v121, v0
	v_mov_b32_e32 v122, v0
	v_mov_b32_e32 v123, v0
	v_mov_b32_e32 v124, v0
	v_mov_b32_e32 v125, v0
	v_mov_b32_e32 v126, v0
	v_mov_b32_e32 v127, v0
	s_barrier
	s_branch .LBB0_202

; template <int EPI>
; __device__ void gemm8_phase(const Params& p, const u16* __restrict__ A, const u16* __restrict__ Bt, const int K, const int nN,
;                             unsigned char* smem, const int rep) {
;     ...
;   for (int tile0 = blockIdx.x; tile0 < nwg * rep; tile0 += gridDim.x) {
;     const int tile = tile0 % nwg;
;     int wgid = tile;
;     {
;       int q = nwg / NXCD, r = nwg % NXCD, xcd = wgid % NXCD, off = wgid / NXCD;
;       wgid = (xcd < r ? xcd * (q + 1) : r * (q + 1) + (xcd - r) * q) + off;
;     }
;     const int nig = WGM * nN, gid = wgid / nig, fm = gid * WGM, gsz = min(nM - fm, WGM);
;     const int pm = fm + ((wgid % nig) % gsz), pn = (wgid % nig) / gsz, brow = pm * BM8, bcol = pn * BM8;
;     ...
;     STAGE(SB(0, 0), Bt, bcol, 0); STAGE(SA(0, 0), A, brow, 0);
;     STAGE(SB(0, 1), Bt, bcol + HALF, 0); STAGE(SA(0, 1), A, brow + HALF, 0);
.Lg5_readback:
	s_waitcnt lgkmcnt(0)
	s_barrier
	v_readlane_b32 s7, v255, 6
	v_lshrrev_b32_e32 v178, 5, v156
	v_and_b32_e32 v176, 31, v156
	s_lshl_b32 s7, s7, 5
	v_add_u32_e32 v178, s7, v178
	v_lshlrev_b32_e32 v176, 4, v176
	v_add_u32_e32 v177, s30, v178
	v_mul_u32_u24_e32 v177, 0x3080, v177
	v_mul_u32_u24_e32 v178, 0x210, v178
	v_add3_u32 v177, v177, v176, s33
	v_add_u32_e32 v176, v178, v176
	ds_read_b128 v[0:3], v176
	ds_read_b128 v[4:7], v176 offset:1056
	ds_read_b128 v[8:11], v176 offset:2112
	ds_read_b128 v[12:15], v176 offset:3168
	ds_read_b128 v[16:19], v176 offset:4224
	ds_read_b128 v[20:23], v176 offset:5280
	ds_read_b128 v[24:27], v176 offset:6336
	ds_read_b128 v[28:31], v176 offset:7392
	ds_read_b128 v[32:35], v176 offset:8448
	ds_read_b128 v[36:39], v176 offset:9504
	ds_read_b128 v[40:43], v176 offset:10560
	ds_read_b128 v[44:47], v176 offset:11616
	ds_read_b128 v[48:51], v176 offset:12672
	ds_read_b128 v[52:55], v176 offset:13728
	ds_read_b128 v[56:59], v176 offset:14784
	ds_read_b128 v[60:63], v176 offset:15840
	s_waitcnt lgkmcnt(0)
	s_barrier
	s_add_i32 s47, s47, s96
	s_cmp_lt_i32 s47, s39
	s_cbranch_scc0 .Lstg5
	s_mul_hi_i32 s0, s47, 0xa0a0a0a1
	s_add_i32 s0, s0, s47
	s_lshr_b32 s1, s0, 31
	s_lshr_b32 s0, s0, 10
	s_add_i32 s0, s0, s1
	s_mulk_i32 s0, 0x660
	s_sub_i32 s0, s47, s0
	s_sext_i32_i16 s1, s0
	s_bfe_u32 s1, s1, 0x3001c
	s_add_i32 s1, s0, s1
	s_sext_i32_i16 s4, s1
	s_and_b32 s1, s1, 0xfff8
	s_sub_i32 s0, s0, s1
	s_ashr_i32 s4, s4, 3
	s_sext_i32_i16 s1, s0
	s_cmp_lt_i32 s1, 0
	s_cselect_b32 s1, s42, 0xcc
	s_mul_i32 s0, s1, s0
	s_add_i32 s0, s0, s4
	s_sext_i32_i16 s1, s0
	s_mulk_i32 s1, 0x2aab
	s_lshr_b32 s4, s1, 31
	s_ashr_i32 s7, s1, 20
	s_add_i32 s7, s7, s4
	s_mul_i32 s1, s7, 0x60
	s_sub_i32 s0, s0, s1
	s_bfe_i32 s1, s0, 0x80000
	s_bfe_u32 s1, s1, 0x2000d
	s_add_i32 s1, s0, s1
	s_bfe_i32 s5, s1, 0x80000
	s_and_b32 s1, s1, 0xfc
	s_sext_i32_i16 s5, s5
	s_sub_i32 s1, s0, s1
	s_sext_i32_i8 s30, s1
	s_ashr_i32 s1, s5, 2
	v_readfirstlane_b32 s5, v147
	s_lshl_b32 s4, s7, 2
	s_lshl_b32 s6, s1, 19
	s_mov_b32 m0, s5
	v_readfirstlane_b32 s5, v148
	s_add_i32 s4, s4, s30
	buffer_load_dwordx4 v143, s[12:15], s6 offen lds
	s_mov_b32 m0, s5
	v_readfirstlane_b32 s31, v142
	buffer_load_dwordx4 v145, s[12:15], s6 offen lds
	s_lshl_b32 s5, s4, 19
	s_mov_b32 m0, s31
	v_readfirstlane_b32 s31, v144
	buffer_load_dwordx4 v143, s[8:11], s5 offen lds
	s_mov_b32 m0, s31
	v_readfirstlane_b32 s33, v149
	buffer_load_dwordx4 v145, s[8:11], s5 offen lds
	s_or_b32 s31, s6, 0x40000
	s_mov_b32 m0, s33
	v_readfirstlane_b32 s33, v150
	buffer_load_dwordx4 v143, s[12:15], s31 offen lds
	s_mov_b32 m0, s33
	v_readfirstlane_b32 s33, v151
	buffer_load_dwordx4 v145, s[12:15], s31 offen lds
	s_or_b32 s31, s5, 0x40000
	s_mov_b32 m0, s33
	v_readfirstlane_b32 s33, v152
	buffer_load_dwordx4 v143, s[8:11], s31 offen lds
	s_mov_b32 m0, s33
	s_and_b64 vcc, exec, s[2:3]
	buffer_load_dwordx4 v145, s[8:11], s31 offen lds
.Lstg5:
	global_store_dwordx4 v177, v[0:3], s[24:25]
	v_add_u32_e32 v177, 0x6100, v177
	global_store_dwordx4 v177, v[4:7], s[24:25]
	v_add_u32_e32 v177, 0x6100, v177
	global_store_dwordx4 v177, v[8:11], s[24:25]
	v_add_u32_e32 v177, 0x6100, v177
	global_store_dwordx4 v177, v[12:15], s[24:25]
	v_add_u32_e32 v177, 0x6100, v177
	global_store_dwordx4 v177, v[16:19], s[24:25]
	v_add_u32_e32 v177, 0x6100, v177
	global_store_dwordx4 v177, v[20:23], s[24:25]
	v_add_u32_e32 v177, 0x6100, v177
	global_store_dwordx4 v177, v[24:27], s[24:25]
	v_add_u32_e32 v177, 0x6100, v177
	global_store_dwordx4 v177, v[28:31], s[24:25]
	v_add_u32_e32 v177, 0x6100, v177
	global_store_dwordx4 v177, v[32:35], s[24:25]
	v_add_u32_e32 v177, 0x6100, v177
	global_store_dwordx4 v177, v[36:39], s[24:25]
	v_add_u32_e32 v177, 0x6100, v177
	global_store_dwordx4 v177, v[40:43], s[24:25]
	v_add_u32_e32 v177, 0x6100, v177
	global_store_dwordx4 v177, v[44:47], s[24:25]
	v_add_u32_e32 v177, 0x6100, v177
	global_store_dwordx4 v177, v[48:51], s[24:25]
	v_add_u32_e32 v177, 0x6100, v177
	global_store_dwordx4 v177, v[52:55], s[24:25]
	v_add_u32_e32 v177, 0x6100, v177
	global_store_dwordx4 v177, v[56:59], s[24:25]
	v_add_u32_e32 v177, 0x6100, v177
	global_store_dwordx4 v177, v[60:63], s[24:25]
	s_cmp_lt_i32 s47, s39
	s_cbranch_scc0 .LBB0_1220
	s_and_b64 vcc, exec, s[2:3]
	s_cbranch_vccnz .Lpf5_201
	s_barrier
; #define WAIT_V(n) asm volatile("s_waitcnt vmcnt(" #n ")" ::: "memory")
; #define BAR __builtin_amdgcn_s_barrier()
; template <int EPI>
; __device__ void gemm8_phase(const Params& p, const u16* __restrict__ A, const u16* __restrict__ Bt, const int K, const int nN,
;                             unsigned char* smem, const int rep) {
;     ...
;     if (wr == 1) BAR;
;     WAIT_V(4); BAR;
;     STAGE(SB(1, 0), Bt, bcol, 1); STAGE(SA(1, 0), A, brow, 1); STAGE(SB(1, 1), Bt, bcol + HALF, 1);
;     WAIT_V(6); BAR;
.Lpf5_201:
	v_readfirstlane_b32 s33, v153
	s_or_b32 s31, s6, 0x80
	s_mov_b32 m0, s33
	v_readfirstlane_b32 s33, v154
	s_waitcnt vmcnt(20)
	s_barrier
	buffer_load_dwordx4 v143, s[12:15], s31 offen lds
	s_mov_b32 m0, s33
	v_readfirstlane_b32 s33, v155
	buffer_load_dwordx4 v145, s[12:15], s31 offen lds
	s_or_b32 s31, s5, 0x80
	s_mov_b32 m0, s33
	v_readfirstlane_b32 s33, v157
	buffer_load_dwordx4 v143, s[8:11], s31 offen lds
	s_mov_b32 m0, s33
	v_readfirstlane_b32 s33, v158
	buffer_load_dwordx4 v145, s[8:11], s31 offen lds
	s_or_b32 s31, s6, 0x40080
	s_mov_b32 m0, s33
	v_readfirstlane_b32 s33, v159
	buffer_load_dwordx4 v143, s[12:15], s31 offen lds
	s_mov_b32 m0, s33
	s_lshl_b32 s7, s7, 21
	buffer_load_dwordx4 v145, s[12:15], s31 offen lds
	s_waitcnt vmcnt(22)
	s_lshl_b32 s30, s30, 19
	v_mov_b32_e32 v0, 0
	s_add_i32 s7, s7, s30
	s_mov_b32 s30, -2
	s_mov_b32 s31, 0
	v_mov_b32_e32 v1, v0
	v_mov_b32_e32 v2, v0
	v_mov_b32_e32 v3, v0
	v_mov_b32_e32 v4, v0
	v_mov_b32_e32 v5, v0
	v_mov_b32_e32 v6, v0
	v_mov_b32_e32 v7, v0
	v_mov_b32_e32 v8, v0
	v_mov_b32_e32 v9, v0
	v_mov_b32_e32 v10, v0
	v_mov_b32_e32 v11, v0
	v_mov_b32_e32 v12, v0
	v_mov_b32_e32 v13, v0
	v_mov_b32_e32 v14, v0
	v_mov_b32_e32 v15, v0
	v_mov_b32_e32 v16, v0
	v_mov_b32_e32 v17, v0
	v_mov_b32_e32 v18, v0
	v_mov_b32_e32 v19, v0
	v_mov_b32_e32 v20, v0
	v_mov_b32_e32 v21, v0
	v_mov_b32_e32 v22, v0
	v_mov_b32_e32 v23, v0
	v_mov_b32_e32 v24, v0
	v_mov_b32_e32 v25, v0
	v_mov_b32_e32 v26, v0
	v_mov_b32_e32 v27, v0
	v_mov_b32_e32 v28, v0
	v_mov_b32_e32 v29, v0
	v_mov_b32_e32 v30, v0
	v_mov_b32_e32 v31, v0
	v_mov_b32_e32 v32, v0
	v_mov_b32_e32 v33, v0
	v_mov_b32_e32 v34, v0
	v_mov_b32_e32 v35, v0
	v_mov_b32_e32 v36, v0
	v_mov_b32_e32 v37, v0
	v_mov_b32_e32 v38, v0
	v_mov_b32_e32 v39, v0
	v_mov_b32_e32 v40, v0
	v_mov_b32_e32 v41, v0
	v_mov_b32_e32 v42, v0
	v_mov_b32_e32 v43, v0
	v_mov_b32_e32 v44, v0
	v_mov_b32_e32 v45, v0
	v_mov_b32_e32 v46, v0
	v_mov_b32_e32 v47, v0
	v_mov_b32_e32 v48, v0
	v_mov_b32_e32 v49, v0
	v_mov_b32_e32 v50, v0
	v_mov_b32_e32 v51, v0
	v_mov_b32_e32 v52, v0
	v_mov_b32_e32 v53, v0
	v_mov_b32_e32 v54, v0
	v_mov_b32_e32 v55, v0
	v_mov_b32_e32 v56, v0
	v_mov_b32_e32 v57, v0
	v_mov_b32_e32 v58, v0
	v_mov_b32_e32 v59, v0
	v_mov_b32_e32 v60, v0
	v_mov_b32_e32 v61, v0
	v_mov_b32_e32 v62, v0
	v_mov_b32_e32 v63, v0
	v_mov_b32_e32 v64, v0
	v_mov_b32_e32 v65, v0
	v_mov_b32_e32 v66, v0
	v_mov_b32_e32 v67, v0
	v_mov_b32_e32 v68, v0
	v_mov_b32_e32 v69, v0
	v_mov_b32_e32 v70, v0
	v_mov_b32_e32 v71, v0
	v_mov_b32_e32 v72, v0
	v_mov_b32_e32 v73, v0
	v_mov_b32_e32 v74, v0
	v_mov_b32_e32 v75, v0
	v_mov_b32_e32 v76, v0
	v_mov_b32_e32 v77, v0
	v_mov_b32_e32 v78, v0
	v_mov_b32_e32 v79, v0
	v_mov_b32_e32 v80, v0
	v_mov_b32_e32 v81, v0
	v_mov_b32_e32 v82, v0
	v_mov_b32_e32 v83, v0
	v_mov_b32_e32 v84, v0
	v_mov_b32_e32 v85, v0
	v_mov_b32_e32 v86, v0
	v_mov_b32_e32 v87, v0
	v_mov_b32_e32 v88, v0
	v_mov_b32_e32 v89, v0
	v_mov_b32_e32 v90, v0
	v_mov_b32_e32 v91, v0
	v_mov_b32_e32 v92, v0
	v_mov_b32_e32 v93, v0
	v_mov_b32_e32 v94, v0
	v_mov_b32_e32 v95, v0
	v_mov_b32_e32 v96, v0
	v_mov_b32_e32 v97, v0
	v_mov_b32_e32 v98, v0
	v_mov_b32_e32 v99, v0
	v_mov_b32_e32 v100, v0
	v_mov_b32_e32 v101, v0
	v_mov_b32_e32 v102, v0
	v_mov_b32_e32 v103, v0
	v_mov_b32_e32 v104, v0
	v_mov_b32_e32 v105, v0
	v_mov_b32_e32 v106, v0
	v_mov_b32_e32 v107, v0
	v_mov_b32_e32 v108, v0
	v_mov_b32_e32 v109, v0
	v_mov_b32_e32 v110, v0
	v_mov_b32_e32 v111, v0
	v_mov_b32_e32 v112, v0
	v_mov_b32_e32 v113, v0
	v_mov_b32_e32 v114, v0
	v_mov_b32_e32 v115, v0
	v_mov_b32_e32 v116, v0
	v_mov_b32_e32 v117, v0
	v_mov_b32_e32 v118, v0
	v_mov_b32_e32 v119, v0
	v_mov_b32_e32 v120, v0
	v_mov_b32_e32 v121, v0
	v_mov_b32_e32 v122, v0
	v_mov_b32_e32 v123, v0
	v_mov_b32_e32 v124, v0
	v_mov_b32_e32 v125, v0
	v_mov_b32_e32 v126, v0
	v_mov_b32_e32 v127, v0
	s_barrier
	s_branch .LBB0_1061
